# v5 + MLA PV stage: v_exp interleaved 1:1 with row-sum adds (trans/non-trans alternate) instead of 8 exps in a row
# speedup vs baseline: 1.0077x; 1.0008x over previous
; #define LAS __attribute__((address_space(3)))
; #define MFMA32(a, b, c) __builtin_amdgcn_mfma_f32_32x32x16_bf16((a), (b), (c), 0, 0, 0)
; DI s16x4 trread(LAS const char* p) { return __builtin_bit_cast(s16x4, __builtin_amdgcn_ds_read_tr16_b64_v4i16((LAS v4i16_t*)p)); }
; DI bf16x8 cat8(s16x4 lo, s16x4 hi) { return __builtin_shufflevector(lo, hi, 0, 1, 2, 3, 4, 5, 6, 7); }
; DI void mla_phase(const Args& A, LAS unsigned char* lds, int i, const int wv) {
;     ...
;             float ls = 0.f;
; #pragma unroll
;             for (int kt = 0; kt < 4; ++kt)
; #pragma unroll
;                 for (int rg = 0; rg < 16; ++rg) { p[kt][rg] = __builtin_amdgcn_exp2f(p[kt][rg]); ls += p[kt][rg]; }
;             l += ls;
; #pragma unroll
;             for (int kt = 0; kt < 4; ++kt)
; #pragma unroll
;                 for (int s = 0; s < 2; ++s) { const bf16x8 pb = pack8(p[kt], s);
; #pragma unroll
;                     for (int dt = 0; dt < 2; ++dt) { LAS const char* ad = (LAS const char*)vbp + (32 * kt + 16 * s + 4 * h + q_) * 144 + (32 * dt + 16 * blk) * 2 + 8 * p_;
;                         const bf16x8 va = cat8(trread(ad), trread(ad + 8 * 144)); o[dt] = MFMA32(va, pb, o[dt]); } }
.Lmla_a_norescale:
	v_exp_f32_e32 v112, v112
	v_exp_f32_e32 v113, v113
	v_exp_f32_e32 v114, v114
	v_add_f32_e32 v14, v112, v113
	v_exp_f32_e32 v115, v115
	v_cvt_pk_bf16_f32 v10, v112, v113
	v_exp_f32_e32 v116, v116
	v_add_f32_e32 v15, v114, v115
	v_exp_f32_e32 v117, v117
	v_add_f32_e32 v14, v14, v116
	v_exp_f32_e32 v118, v118
	v_add_f32_e32 v15, v15, v117
	v_exp_f32_e32 v119, v119
	v_add_f32_e32 v14, v14, v118
	v_add_f32_e32 v15, v15, v119
	v_cvt_pk_bf16_f32 v11, v114, v115
	v_cvt_pk_bf16_f32 v12, v116, v117
	v_cvt_pk_bf16_f32 v13, v118, v119
	ds_read_b64_tr_b16 v[116:117], v182 offset:28928
	ds_read_b64_tr_b16 v[118:119], v182 offset:30080
	v_exp_f32_e32 v120, v120
	v_exp_f32_e32 v121, v121
	v_add_f32_e32 v14, v14, v120
	v_exp_f32_e32 v122, v122
	v_add_f32_e32 v15, v15, v121
	v_exp_f32_e32 v123, v123
	v_add_f32_e32 v14, v14, v122
	v_exp_f32_e32 v124, v124
	v_add_f32_e32 v15, v15, v123
	v_exp_f32_e32 v125, v125
	v_add_f32_e32 v14, v14, v124
	v_exp_f32_e32 v126, v126
	v_add_f32_e32 v15, v15, v125
	v_exp_f32_e32 v127, v127
	v_add_f32_e32 v14, v14, v126
	v_add_f32_e32 v15, v15, v127
	v_cvt_pk_bf16_f32 v112, v120, v121
	v_cvt_pk_bf16_f32 v113, v122, v123
	v_cvt_pk_bf16_f32 v114, v124, v125
	v_cvt_pk_bf16_f32 v115, v126, v127
	ds_read_b64_tr_b16 v[120:121], v182 offset:28992
	ds_read_b64_tr_b16 v[122:123], v182 offset:30144
	s_nop 0
	v_mfma_f32_32x32x16_bf16 v[32:47], v[2:5], v[10:13], v[32:47]
	ds_read_b64_tr_b16 v[2:3], v182 offset:31232
	ds_read_b64_tr_b16 v[4:5], v182 offset:32384
	v_exp_f32_e32 v96, v96
	v_exp_f32_e32 v97, v97
	v_add_f32_e32 v14, v14, v96
	v_exp_f32_e32 v98, v98
	v_add_f32_e32 v15, v15, v97
	v_exp_f32_e32 v99, v99
	v_add_f32_e32 v14, v14, v98
	v_exp_f32_e32 v100, v100
	v_mfma_f32_32x32x16_bf16 v[16:31], v[6:9], v[10:13], v[16:31]
	ds_read_b64_tr_b16 v[6:7], v182 offset:31296
	ds_read_b64_tr_b16 v[8:9], v182 offset:32448
	v_add_f32_e32 v15, v15, v99
	v_exp_f32_e32 v101, v101
	v_add_f32_e32 v14, v14, v100
	v_exp_f32_e32 v102, v102
	v_add_f32_e32 v15, v15, v101
	v_exp_f32_e32 v103, v103
	v_add_f32_e32 v14, v14, v102
	v_add_f32_e32 v15, v15, v103
	v_cvt_pk_bf16_f32 v124, v96, v97
	v_cvt_pk_bf16_f32 v125, v98, v99
	v_cvt_pk_bf16_f32 v126, v100, v101
	v_cvt_pk_bf16_f32 v127, v102, v103
	s_waitcnt lgkmcnt(6)
	v_mfma_f32_32x32x16_bf16 v[32:47], v[116:119], v[112:115], v[32:47]
	ds_read_b64_tr_b16 v[116:117], v182 offset:33536
	ds_read_b64_tr_b16 v[118:119], v182 offset:34688
	v_exp_f32_e32 v104, v104
	v_exp_f32_e32 v105, v105
	v_add_f32_e32 v14, v14, v104
	v_exp_f32_e32 v106, v106
	v_add_f32_e32 v15, v15, v105
	v_exp_f32_e32 v107, v107
	v_add_f32_e32 v14, v14, v106
	v_exp_f32_e32 v108, v108
	v_add_f32_e32 v15, v15, v107
	v_exp_f32_e32 v109, v109
	s_waitcnt lgkmcnt(6)
	v_mfma_f32_32x32x16_bf16 v[16:31], v[120:123], v[112:115], v[16:31]
	ds_read_b64_tr_b16 v[120:121], v182 offset:33600
	ds_read_b64_tr_b16 v[122:123], v182 offset:34752
	v_add_f32_e32 v14, v14, v108
	v_exp_f32_e32 v110, v110
	v_add_f32_e32 v15, v15, v109
	v_exp_f32_e32 v111, v111
	v_add_f32_e32 v14, v14, v110
	v_add_f32_e32 v15, v15, v111
	v_cvt_pk_bf16_f32 v10, v104, v105
	v_cvt_pk_bf16_f32 v11, v106, v107
	v_cvt_pk_bf16_f32 v12, v108, v109
	v_cvt_pk_bf16_f32 v13, v110, v111
	s_waitcnt lgkmcnt(6)
	v_mfma_f32_32x32x16_bf16 v[32:47], v[2:5], v[124:127], v[32:47]
	ds_read_b64_tr_b16 v[2:3], v182 offset:35840
	ds_read_b64_tr_b16 v[4:5], v182 offset:36992
	v_exp_f32_e32 v80, v80
	v_exp_f32_e32 v81, v81
	v_add_f32_e32 v14, v14, v80
	v_exp_f32_e32 v82, v82
	v_add_f32_e32 v15, v15, v81
	v_exp_f32_e32 v83, v83
	v_add_f32_e32 v14, v14, v82
	v_exp_f32_e32 v84, v84
	v_add_f32_e32 v15, v15, v83
	v_exp_f32_e32 v85, v85
	s_waitcnt lgkmcnt(6)
	v_mfma_f32_32x32x16_bf16 v[16:31], v[6:9], v[124:127], v[16:31]
	ds_read_b64_tr_b16 v[6:7], v182 offset:35904
	ds_read_b64_tr_b16 v[8:9], v182 offset:37056
	v_add_f32_e32 v14, v14, v84
	v_exp_f32_e32 v86, v86
	v_add_f32_e32 v15, v15, v85
	v_exp_f32_e32 v87, v87
	v_add_f32_e32 v14, v14, v86
	v_add_f32_e32 v15, v15, v87
	v_cvt_pk_bf16_f32 v112, v80, v81
	v_cvt_pk_bf16_f32 v113, v82, v83
	v_cvt_pk_bf16_f32 v114, v84, v85
	v_cvt_pk_bf16_f32 v115, v86, v87
	s_waitcnt lgkmcnt(6)
; #define LAS __attribute__((address_space(3)))
; #define MFMA32(a, b, c) __builtin_amdgcn_mfma_f32_32x32x16_bf16((a), (b), (c), 0, 0, 0)
; DI s16x4 trread(LAS const char* p) { return __builtin_bit_cast(s16x4, __builtin_amdgcn_ds_read_tr16_b64_v4i16((LAS v4i16_t*)p)); }
; DI bf16x8 cat8(s16x4 lo, s16x4 hi) { return __builtin_shufflevector(lo, hi, 0, 1, 2, 3, 4, 5, 6, 7); }
; DI void mla_phase(const Args& A, LAS unsigned char* lds, int i, const int wv) {
;     ...
;             float ls = 0.f;
; #pragma unroll
;             for (int kt = 0; kt < 4; ++kt)
; #pragma unroll
;                 for (int rg = 0; rg < 16; ++rg) { p[kt][rg] = __builtin_amdgcn_exp2f(p[kt][rg]); ls += p[kt][rg]; }
;             l += ls;
; #pragma unroll
;             for (int kt = 0; kt < 4; ++kt)
; #pragma unroll
;                 for (int s = 0; s < 2; ++s) { const bf16x8 pb = pack8(p[kt], s);
; #pragma unroll
;                     for (int dt = 0; dt < 2; ++dt) { LAS const char* ad = (LAS const char*)vbp + (32 * kt + 16 * s + 4 * h + q_) * 144 + (32 * dt + 16 * blk) * 2 + 8 * p_;
;                         const bf16x8 va = cat8(trread(ad), trread(ad + 8 * 144)); o[dt] = MFMA32(va, pb, o[dt]); } }
;             if (j + 1 < 64) MLA_ST((j + 1) & 1);
	v_mfma_f32_32x32x16_bf16 v[32:47], v[116:119], v[10:13], v[32:47]
	ds_read_b64_tr_b16 v[116:117], v182 offset:38144
	ds_read_b64_tr_b16 v[118:119], v182 offset:39296
	v_exp_f32_e32 v88, v88
	v_exp_f32_e32 v89, v89
	v_add_f32_e32 v14, v14, v88
	v_exp_f32_e32 v90, v90
	v_add_f32_e32 v15, v15, v89
	v_exp_f32_e32 v91, v91
	v_add_f32_e32 v14, v14, v90
	v_exp_f32_e32 v92, v92
	v_add_f32_e32 v15, v15, v91
	v_exp_f32_e32 v93, v93
	s_waitcnt lgkmcnt(6)
	v_mfma_f32_32x32x16_bf16 v[16:31], v[120:123], v[10:13], v[16:31]
	ds_read_b64_tr_b16 v[120:121], v182 offset:38208
	ds_read_b64_tr_b16 v[122:123], v182 offset:39360
	v_add_f32_e32 v14, v14, v92
	v_exp_f32_e32 v94, v94
	v_add_f32_e32 v15, v15, v93
	v_exp_f32_e32 v95, v95
	v_add_f32_e32 v14, v14, v94
	v_add_f32_e32 v15, v15, v95
	v_cvt_pk_bf16_f32 v124, v88, v89
	v_cvt_pk_bf16_f32 v125, v90, v91
	v_cvt_pk_bf16_f32 v126, v92, v93
	v_cvt_pk_bf16_f32 v127, v94, v95
	s_waitcnt lgkmcnt(6)
	v_mfma_f32_32x32x16_bf16 v[32:47], v[2:5], v[112:115], v[32:47]
	ds_read_b64_tr_b16 v[2:3], v182 offset:40448
	ds_read_b64_tr_b16 v[4:5], v182 offset:41600
	v_exp_f32_e32 v64, v64
	v_exp_f32_e32 v65, v65
	v_add_f32_e32 v14, v14, v64
	v_exp_f32_e32 v66, v66
	v_add_f32_e32 v15, v15, v65
	v_exp_f32_e32 v67, v67
	v_add_f32_e32 v14, v14, v66
	v_exp_f32_e32 v68, v68
	v_add_f32_e32 v15, v15, v67
	v_exp_f32_e32 v69, v69
	s_waitcnt lgkmcnt(6)
	v_mfma_f32_32x32x16_bf16 v[16:31], v[6:9], v[112:115], v[16:31]
	ds_read_b64_tr_b16 v[6:7], v182 offset:40512
	ds_read_b64_tr_b16 v[8:9], v182 offset:41664
	v_add_f32_e32 v14, v14, v68
	v_exp_f32_e32 v70, v70
	v_add_f32_e32 v15, v15, v69
	v_exp_f32_e32 v71, v71
	v_add_f32_e32 v14, v14, v70
	v_add_f32_e32 v15, v15, v71
	v_cvt_pk_bf16_f32 v10, v64, v65
	v_cvt_pk_bf16_f32 v11, v66, v67
	v_cvt_pk_bf16_f32 v12, v68, v69
	v_cvt_pk_bf16_f32 v13, v70, v71
	s_waitcnt lgkmcnt(6)
	v_mfma_f32_32x32x16_bf16 v[32:47], v[116:119], v[124:127], v[32:47]
	ds_read_b64_tr_b16 v[116:117], v182 offset:42752
	ds_read_b64_tr_b16 v[118:119], v182 offset:43904
	v_exp_f32_e32 v72, v72
	v_exp_f32_e32 v73, v73
	v_add_f32_e32 v14, v14, v72
	v_exp_f32_e32 v74, v74
	v_add_f32_e32 v15, v15, v73
	v_exp_f32_e32 v75, v75
	v_add_f32_e32 v14, v14, v74
	v_exp_f32_e32 v76, v76
	v_add_f32_e32 v15, v15, v75
	v_exp_f32_e32 v77, v77
	s_waitcnt lgkmcnt(6)
	v_mfma_f32_32x32x16_bf16 v[16:31], v[120:123], v[124:127], v[16:31]
	ds_read_b64_tr_b16 v[120:121], v182 offset:42816
	ds_read_b64_tr_b16 v[122:123], v182 offset:43968
	v_add_f32_e32 v14, v14, v76
	v_exp_f32_e32 v78, v78
	v_add_f32_e32 v15, v15, v77
	v_exp_f32_e32 v79, v79
	v_add_f32_e32 v14, v14, v78
	v_add_f32_e32 v15, v15, v79
	v_cvt_pk_bf16_f32 v112, v72, v73
	v_cvt_pk_bf16_f32 v113, v74, v75
	v_cvt_pk_bf16_f32 v114, v76, v77
	v_cvt_pk_bf16_f32 v115, v78, v79
	s_nop 0
	s_waitcnt lgkmcnt(6)
	v_mfma_f32_32x32x16_bf16 v[32:47], v[2:5], v[10:13], v[32:47]
	v_add_f32_e32 v14, v14, v15
	s_waitcnt lgkmcnt(4)
	v_mfma_f32_32x32x16_bf16 v[16:31], v[6:9], v[10:13], v[16:31]
	v_add_f32_e32 v0, v0, v14
	s_waitcnt lgkmcnt(2)
	v_mfma_f32_32x32x16_bf16 v[32:47], v[116:119], v[112:115], v[32:47]
	s_waitcnt lgkmcnt(0)
	v_mfma_f32_32x32x16_bf16 v[16:31], v[120:123], v[112:115], v[16:31]
	s_add_i32 s7, s7, 1
	s_cmp_eq_u32 s7, 64
	s_cbranch_scc1 .Lmla_a_nost
	s_bitcmp1_b32 s7, 0
	s_cselect_b32 s2, 0xb000, 0
	v_add3_u32 v183, s2, v251, v252
	s_waitcnt vmcnt(4)
	ds_write_b128 v183, v[128:131]
	v_add3_u32 v242, s2, v239, v172
	s_waitcnt vmcnt(3)
	ds_write_b128 v242, v[132:135]
	v_add3_u32 v183, s2, v173, v174
	s_waitcnt vmcnt(2)
	ds_write_b128 v183, v[136:139]
	v_add_u32_e32 v242, s2, v246
	v_add_u32_e32 v183, v242, v175
	v_add_u32_e32 v242, v242, v234
	s_waitcnt vmcnt(1)
	ds_write_b128 v183, v[140:143] offset:26624
	s_waitcnt vmcnt(0)
	ds_write_b128 v242, v[144:147] offset:26624
